# v28 + HGRN chunk loops: counted lgkmcnt waits at first use instead of lgkmcnt(0) after the 21-read burst
# speedup vs baseline: 1.0018x; 1.0018x over previous
.LBB0_751:
	s_mul_i32 s10, s20, 37
	s_bfe_u32 s11, s10, 0x80008
	s_lshr_b32 s10, s10, 8
	s_sub_i32 s10, s20, s10
	s_bfe_u32 s10, s10, 0x70001
	s_add_i32 s10, s10, s11
	s_bfe_u32 s10, s10, 0x60002
	s_mul_i32 s10, s10, 7
	s_sub_i32 s10, s20, s10
	s_and_b32 s10, s10, 0xff
	s_mulk_i32 s10, 0x4400
	s_add_i32 s10, s10, 0
	v_add_u32_e32 v32, s10, v57
	v_add_u32_e32 v33, v32, v67
	ds_read2st64_b64 v[80:83], v33 offset1:8
	v_add_u32_e32 v33, v32, v68
	ds_read2st64_b64 v[84:87], v33 offset1:8
	v_add_u32_e32 v33, v32, v69
	ds_read2st64_b64 v[88:91], v33 offset1:8
	v_add_u32_e32 v33, v32, v70
	ds_read2st64_b64 v[92:95], v33 offset1:8
	v_add_u32_e32 v33, v32, v71
	ds_read2st64_b64 v[96:99], v33 offset1:8
	v_add_u32_e32 v33, v32, v72
	ds_read2st64_b64 v[100:103], v33 offset1:8
	v_add_u32_e32 v33, v32, v73
	v_add_u32_e32 v32, v32, v74
	ds_read2st64_b64 v[108:111], v32 offset1:8
	v_add_u32_e32 v32, s10, v55
	v_add3_u32 v32, v32, v61, v53
	ds_read_b64 v[62:63], v32 offset:12288
	v_add_u32_e32 v32, s10, v60
	v_add3_u32 v32, v32, v61, v53
	v_add_u32_e32 v36, s10, v66
	ds_read2st64_b64 v[104:107], v33 offset1:8
	ds_read_b128 v[112:115], v36 offset:16384
	ds_read_b128 v[116:119], v36 offset:16448
	ds_read2st64_b64 v[120:123], v32 offset0:16 offset1:17
	ds_read2st64_b64 v[124:127], v32 offset0:18 offset1:19
	ds_read_b128 v[128:131], v36 offset:16512
	ds_read_b128 v[132:135], v36 offset:16576
	ds_read_b128 v[136:139], v36 offset:16640
	ds_read_b128 v[140:143], v36 offset:16704
	ds_read2st64_b64 v[162:165], v32 offset0:20 offset1:21
	ds_read2st64_b64 v[32:35], v32 offset0:22 offset1:23
	ds_read_b128 v[40:43], v36 offset:16768
	ds_read_b128 v[36:39], v36 offset:16832
	s_waitcnt lgkmcnt(15)
	v_mov_b32_e32 v170, v82
	v_mov_b32_e32 v171, v83
	v_mov_b32_e32 v172, v86
	v_mov_b32_e32 v173, v87
	v_mov_b32_e32 v82, v84
	v_mov_b32_e32 v83, v85
	s_and_b64 s[10:11], s[40:41], exec
	s_cselect_b32 s10, s20, s21
	v_mfma_f32_16x16x32_bf16 v[84:87], v[170:173], v[80:83], 0
	v_mov_b32_e32 v170, v90
	v_mov_b32_e32 v171, v91
	v_mov_b32_e32 v172, v94
	v_mov_b32_e32 v173, v95
	v_mov_b32_e32 v90, v92
	v_mov_b32_e32 v91, v93
	v_mov_b32_e32 v92, v98
	v_mov_b32_e32 v93, v99
	v_mov_b32_e32 v94, v102
	v_mov_b32_e32 v95, v103
	v_mfma_f32_16x16x32_bf16 v[84:87], v[170:173], v[88:91], v[84:87]
	v_mov_b32_e32 v98, v100
	v_mov_b32_e32 v99, v101
	s_lshl_b32 s10, s10, 4
	s_add_i32 s10, s10, s19
	v_mfma_f32_16x16x32_bf16 v[84:87], v[92:95], v[96:99], v[84:87]
	s_waitcnt lgkmcnt(12)
	v_mov_b32_e32 v92, v106
	v_mov_b32_e32 v93, v107
	v_mov_b32_e32 v94, v110
	v_mov_b32_e32 v95, v111
	v_mov_b32_e32 v106, v108
	v_mov_b32_e32 v107, v109
	s_add_i32 s21, s21, -1
	s_add_i32 s20, s20, 1
	v_mfma_f32_16x16x32_bf16 v[84:87], v[92:95], v[104:107], v[84:87]
	v_cvt_pk_bf16_f32 v92, v20, v21
	v_cvt_pk_bf16_f32 v93, v22, v23
	v_cvt_pk_bf16_f32 v94, v28, v29
	v_cvt_pk_bf16_f32 v95, v30, v31
	s_waitcnt lgkmcnt(10)
	v_pk_mul_f32 v[22:23], v[22:23], v[114:115]
	s_nop 2
	v_cndmask_b32_e64 v65, v87, 0, s[42:43]
	v_cndmask_b32_e64 v79, v86, 0, s[4:5]
	v_cndmask_b32_e64 v85, v85, 0, s[6:7]
	v_cndmask_b32_e64 v84, v84, 0, s[8:9]
	v_cvt_pk_bf16_f32 v84, v84, v85
	v_cvt_pk_bf16_f32 v85, v79, v65
	v_mov_b32_e32 v86, v64
	v_mov_b32_e32 v87, v64
	v_mov_b32_e32 v65, v64
	v_pk_mul_f32 v[20:21], v[20:21], v[112:113]
	v_pk_mul_f32 v[30:31], v[30:31], v[118:119]
	v_mfma_f32_16x16x32_bf16 v[84:87], v[84:87], v[62:65], 0
	v_mul_f32_e64 v28, v28, v116
	v_mul_f32_e64 v29, v29, v117
	s_cmp_lg_u32 s20, 16
	v_mfma_f32_16x16x32_bf16 v[80:83], v[80:83], v[92:95], v[84:87]
	s_nop 3
	v_cvt_pk_bf16_f32 v84, v16, v17
	v_cvt_pk_bf16_f32 v85, v18, v19
	v_cvt_pk_bf16_f32 v86, v24, v25
	v_cvt_pk_bf16_f32 v87, v26, v27
	s_waitcnt lgkmcnt(7)
	v_pk_mul_f32 v[18:19], v[18:19], v[130:131]
	v_pk_mul_f32 v[16:17], v[16:17], v[128:129]
	v_mfma_f32_16x16x32_bf16 v[80:83], v[88:91], v[84:87], v[80:83]
	v_cvt_pk_bf16_f32 v84, v8, v9
	v_cvt_pk_bf16_f32 v85, v10, v11
	v_cvt_pk_bf16_f32 v86, v12, v13
	v_cvt_pk_bf16_f32 v87, v14, v15
	v_mov_b32_e32 v88, v124
	v_mov_b32_e32 v89, v125
	v_mfma_f32_16x16x32_bf16 v[80:83], v[96:99], v[84:87], v[80:83]
	v_cvt_pk_bf16_f32 v84, v0, v1
	v_cvt_pk_bf16_f32 v85, v2, v3
	v_cvt_pk_bf16_f32 v86, v4, v5
	v_cvt_pk_bf16_f32 v87, v6, v7
	v_mov_b32_e32 v90, v64
	v_mov_b32_e32 v91, v64
	v_mfma_f32_16x16x32_bf16 v[80:83], v[104:107], v[84:87], v[80:83]
	v_add_u32_e32 v84, s10, v75
	v_ashrrev_i32_e32 v85, 31, v84
	v_lshlrev_b64 v[84:85], 11, v[84:85]
	v_lshl_add_u64 v[84:85], v[58:59], 0, v[84:85]
	v_mov_b32_e32 v86, v64
	s_nop 2
	global_store_dword v[84:85], v80, off
	v_add_u32_e32 v84, s10, v76
	v_ashrrev_i32_e32 v85, 31, v84
	v_lshlrev_b64 v[84:85], 11, v[84:85]
	v_lshl_add_u64 v[84:85], v[58:59], 0, v[84:85]
	global_store_dword v[84:85], v81, off
	v_mov_b32_e32 v84, v120
	v_mov_b32_e32 v85, v121
	v_mov_b32_e32 v87, v64
	v_mfma_f32_16x16x32_bf16 v[16:19], v[88:91], v[62:65], v[16:19]
	s_waitcnt lgkmcnt(3)
	v_mov_b32_e32 v88, v162
	v_mov_b32_e32 v89, v163
	v_pk_mul_f32 v[26:27], v[26:27], v[134:135]
	v_mfma_f32_16x16x32_bf16 v[20:23], v[84:87], v[62:65], v[20:23]
	v_mov_b32_e32 v84, v122
	v_mov_b32_e32 v85, v123
	v_pk_mul_f32 v[24:25], v[24:25], v[132:133]
	v_pk_mul_f32 v[10:11], v[10:11], v[138:139]
	v_mfma_f32_16x16x32_bf16 v[28:31], v[84:87], v[62:65], v[28:31]
	v_mov_b32_e32 v84, v126
	v_mov_b32_e32 v85, v127
	v_pk_mul_f32 v[8:9], v[8:9], v[136:137]
	v_add_u32_e32 v80, s10, v77
	v_mfma_f32_16x16x32_bf16 v[24:27], v[84:87], v[62:65], v[24:27]
	v_mov_b32_e32 v84, v164
	v_mov_b32_e32 v85, v165
	v_ashrrev_i32_e32 v81, 31, v80
	v_mfma_f32_16x16x32_bf16 v[8:11], v[88:91], v[62:65], v[8:11]
	s_waitcnt lgkmcnt(0)
	v_mov_b32_e32 v88, v32
	v_mov_b32_e32 v89, v33
	v_mov_b32_e32 v32, v34
	v_mov_b32_e32 v33, v35
	v_mov_b32_e32 v34, v64
	v_mov_b32_e32 v35, v64
	v_lshlrev_b64 v[80:81], 11, v[80:81]
	v_lshl_add_u64 v[80:81], v[58:59], 0, v[80:81]
	v_pk_mul_f32 v[14:15], v[14:15], v[142:143]
	v_pk_mul_f32 v[12:13], v[12:13], v[140:141]
	v_pk_mul_f32 v[2:3], v[2:3], v[42:43]
	v_pk_mul_f32 v[0:1], v[0:1], v[40:41]
	v_pk_mul_f32 v[6:7], v[6:7], v[38:39]
	v_pk_mul_f32 v[4:5], v[4:5], v[36:37]
	global_store_dword v[80:81], v82, off
	v_add_u32_e32 v80, s10, v78
	v_mfma_f32_16x16x32_bf16 v[12:15], v[84:87], v[62:65], v[12:15]
	v_ashrrev_i32_e32 v81, 31, v80
	v_lshlrev_b64 v[80:81], 11, v[80:81]
	v_lshl_add_u64 v[80:81], v[58:59], 0, v[80:81]
	v_mfma_f32_16x16x32_bf16 v[0:3], v[88:91], v[62:65], v[0:3]
	global_store_dword v[80:81], v83, off
	v_mfma_f32_16x16x32_bf16 v[4:7], v[32:35], v[62:65], v[4:7]
	s_cbranch_scc0 .LBB0_764

.LBB0_810:
	s_mul_i32 s10, s12, 37
	s_bfe_u32 s11, s10, 0x80008
	s_lshr_b32 s10, s10, 8
	s_sub_i32 s10, s12, s10
	s_bfe_u32 s10, s10, 0x70001
	s_add_i32 s10, s10, s11
	s_bfe_u32 s10, s10, 0x60002
	s_mul_i32 s10, s10, 7
	s_sub_i32 s10, s12, s10
	s_and_b32 s10, s10, 0xff
	s_mulk_i32 s10, 0x4400
	s_add_i32 s10, s10, 0
	v_add_u32_e32 v32, s10, v54
	v_add_u32_e32 v33, v32, v58
	ds_read2st64_b64 v[74:77], v33 offset1:8
	v_add_u32_e32 v33, v32, v59
	ds_read2st64_b64 v[78:81], v33 offset1:8
	v_add_u32_e32 v33, v32, v60
	ds_read2st64_b64 v[82:85], v33 offset1:8
	v_add_u32_e32 v33, v32, v61
	ds_read2st64_b64 v[86:89], v33 offset1:8
	v_add_u32_e32 v33, v32, v67
	ds_read2st64_b64 v[90:93], v33 offset1:8
	v_add_u32_e32 v33, v32, v69
	ds_read2st64_b64 v[94:97], v33 offset1:8
	v_add_u32_e32 v33, v32, v71
	v_add_u32_e32 v32, v32, v73
	ds_read2st64_b64 v[102:105], v32 offset1:8
	v_add_u32_e32 v32, s10, v53
	v_add3_u32 v32, v32, v56, v52
	ds_read_b64 v[62:63], v32 offset:12288
	v_add_u32_e32 v32, s10, v55
	v_add3_u32 v32, v32, v56, v52
	v_add_u32_e32 v36, s10, v57
	ds_read2st64_b64 v[98:101], v33 offset1:8
	ds_read_b128 v[106:109], v36 offset:16384
	ds_read_b128 v[110:113], v36 offset:16448
	ds_read2st64_b64 v[114:117], v32 offset0:16 offset1:17
	ds_read2st64_b64 v[118:121], v32 offset0:18 offset1:19
	ds_read_b128 v[122:125], v36 offset:16512
	ds_read_b128 v[126:129], v36 offset:16576
	ds_read_b128 v[130:133], v36 offset:16640
	ds_read_b128 v[134:137], v36 offset:16704
	ds_read2st64_b64 v[138:141], v32 offset0:20 offset1:21
	ds_read2st64_b64 v[32:35], v32 offset0:22 offset1:23
	ds_read_b128 v[40:43], v36 offset:16768
	ds_read_b128 v[36:39], v36 offset:16832
	s_waitcnt lgkmcnt(15)
	v_mov_b32_e32 v142, v76
	v_mov_b32_e32 v143, v77
	v_mov_b32_e32 v144, v80
	v_mov_b32_e32 v145, v81
	v_mov_b32_e32 v76, v78
	v_mov_b32_e32 v77, v79
	s_add_i32 s12, s16, s12
	s_and_b64 s[10:11], s[40:41], exec
	v_mfma_f32_16x16x32_bf16 v[78:81], v[142:145], v[74:77], 0
	v_mov_b32_e32 v142, v84
	v_mov_b32_e32 v143, v85
	v_mov_b32_e32 v144, v88
	v_mov_b32_e32 v145, v89
	v_mov_b32_e32 v84, v86
	v_mov_b32_e32 v85, v87
	v_mov_b32_e32 v86, v92
	v_mov_b32_e32 v87, v93
	v_mov_b32_e32 v88, v96
	v_mov_b32_e32 v89, v97
	v_mfma_f32_16x16x32_bf16 v[78:81], v[142:145], v[82:85], v[78:81]
	v_mov_b32_e32 v92, v94
	v_mov_b32_e32 v93, v95
	s_cselect_b32 s10, s12, s18
	s_lshl_b32 s10, s10, 4
	v_mfma_f32_16x16x32_bf16 v[78:81], v[86:89], v[90:93], v[78:81]
	s_waitcnt lgkmcnt(12)
	v_mov_b32_e32 v86, v100
	v_mov_b32_e32 v87, v101
	v_mov_b32_e32 v88, v104
	v_mov_b32_e32 v89, v105
	v_mov_b32_e32 v100, v102
	v_mov_b32_e32 v101, v103
	s_add_i32 s10, s10, s13
	s_add_i32 s18, s18, -1
	v_mfma_f32_16x16x32_bf16 v[78:81], v[86:89], v[98:101], v[78:81]
	v_cvt_pk_bf16_f32 v86, v0, v1
	v_cvt_pk_bf16_f32 v87, v2, v3
	v_cvt_pk_bf16_f32 v88, v4, v5
	v_cvt_pk_bf16_f32 v89, v6, v7
	s_waitcnt lgkmcnt(10)
	v_pk_mul_f32 v[2:3], v[2:3], v[108:109]
	s_nop 2
	v_cndmask_b32_e64 v65, v81, 0, s[42:43]
	v_cndmask_b32_e64 v80, v80, 0, s[4:5]
	v_cndmask_b32_e64 v79, v79, 0, s[6:7]
	v_cndmask_b32_e64 v78, v78, 0, s[8:9]
	v_cvt_pk_bf16_f32 v78, v78, v79
	v_cvt_pk_bf16_f32 v79, v80, v65
	v_mov_b32_e32 v80, v64
	v_mov_b32_e32 v81, v64
	v_mov_b32_e32 v65, v64
	v_pk_mul_f32 v[0:1], v[0:1], v[106:107]
	v_pk_mul_f32 v[6:7], v[6:7], v[112:113]
	v_mfma_f32_16x16x32_bf16 v[78:81], v[78:81], v[62:65], 0
	v_mul_f32_e64 v4, v4, v110
	v_mul_f32_e64 v5, v5, v111
	s_add_i32 s12, s19, -5
	s_cmp_lg_u32 s12, 16
	v_mfma_f32_16x16x32_bf16 v[74:77], v[74:77], v[86:89], v[78:81]
	s_nop 2
	v_cvt_pk_bf16_f32 v78, v8, v9
	v_cvt_pk_bf16_f32 v79, v10, v11
	v_cvt_pk_bf16_f32 v80, v12, v13
	v_cvt_pk_bf16_f32 v81, v14, v15
	s_waitcnt lgkmcnt(7)
	v_pk_mul_f32 v[10:11], v[10:11], v[124:125]
	v_pk_mul_f32 v[8:9], v[8:9], v[122:123]
	v_mfma_f32_16x16x32_bf16 v[74:77], v[82:85], v[78:81], v[74:77]
	v_cvt_pk_bf16_f32 v78, v16, v17
	v_cvt_pk_bf16_f32 v79, v18, v19
	v_cvt_pk_bf16_f32 v80, v20, v21
	v_cvt_pk_bf16_f32 v81, v22, v23
	v_mov_b32_e32 v82, v118
	v_mov_b32_e32 v83, v119
	v_mfma_f32_16x16x32_bf16 v[74:77], v[90:93], v[78:81], v[74:77]
	v_cvt_pk_bf16_f32 v78, v24, v25
	v_cvt_pk_bf16_f32 v79, v26, v27
	v_cvt_pk_bf16_f32 v80, v28, v29
	v_cvt_pk_bf16_f32 v81, v30, v31
	v_mov_b32_e32 v84, v64
	v_mov_b32_e32 v85, v64
	v_mfma_f32_16x16x32_bf16 v[74:77], v[98:101], v[78:81], v[74:77]
	v_add_u32_e32 v78, s10, v66
	v_ashrrev_i32_e32 v79, 31, v78
	v_lshlrev_b64 v[78:79], 11, v[78:79]
	v_lshl_add_u64 v[78:79], v[50:51], 0, v[78:79]
	v_mov_b32_e32 v80, v64
	s_nop 2
	global_store_dword v[78:79], v74, off
	v_add_u32_e32 v78, s10, v68
	v_ashrrev_i32_e32 v79, 31, v78
	v_lshlrev_b64 v[78:79], 11, v[78:79]
	v_lshl_add_u64 v[78:79], v[50:51], 0, v[78:79]
	global_store_dword v[78:79], v75, off
	v_mov_b32_e32 v78, v114
	v_mov_b32_e32 v79, v115
	v_mov_b32_e32 v81, v64
	v_mfma_f32_16x16x32_bf16 v[8:11], v[82:85], v[62:65], v[8:11]
	s_waitcnt lgkmcnt(3)
	v_mov_b32_e32 v82, v138
	v_mov_b32_e32 v83, v139
	v_pk_mul_f32 v[14:15], v[14:15], v[128:129]
	v_mfma_f32_16x16x32_bf16 v[0:3], v[78:81], v[62:65], v[0:3]
	v_mov_b32_e32 v78, v116
	v_mov_b32_e32 v79, v117
	v_pk_mul_f32 v[12:13], v[12:13], v[126:127]
	v_pk_mul_f32 v[18:19], v[18:19], v[132:133]
	v_mfma_f32_16x16x32_bf16 v[4:7], v[78:81], v[62:65], v[4:7]
	v_mov_b32_e32 v78, v120
	v_mov_b32_e32 v79, v121
	v_pk_mul_f32 v[16:17], v[16:17], v[130:131]
	v_add_u32_e32 v74, s10, v70
	v_mfma_f32_16x16x32_bf16 v[12:15], v[78:81], v[62:65], v[12:15]
	v_mov_b32_e32 v78, v140
	v_mov_b32_e32 v79, v141
	v_ashrrev_i32_e32 v75, 31, v74
	v_mfma_f32_16x16x32_bf16 v[16:19], v[82:85], v[62:65], v[16:19]
	s_waitcnt lgkmcnt(0)
	v_mov_b32_e32 v82, v32
	v_mov_b32_e32 v83, v33
	v_mov_b32_e32 v32, v34
	v_mov_b32_e32 v33, v35
	v_mov_b32_e32 v34, v64
	v_mov_b32_e32 v35, v64
	v_lshlrev_b64 v[74:75], 11, v[74:75]
	v_lshl_add_u64 v[74:75], v[50:51], 0, v[74:75]
	v_pk_mul_f32 v[22:23], v[22:23], v[136:137]
	v_pk_mul_f32 v[20:21], v[20:21], v[134:135]
	v_pk_mul_f32 v[26:27], v[26:27], v[42:43]
	v_pk_mul_f32 v[24:25], v[24:25], v[40:41]
	v_pk_mul_f32 v[30:31], v[30:31], v[38:39]
	v_pk_mul_f32 v[28:29], v[28:29], v[36:37]
	global_store_dword v[74:75], v76, off
	v_add_u32_e32 v74, s10, v72
	v_mfma_f32_16x16x32_bf16 v[20:23], v[78:81], v[62:65], v[20:23]
	v_ashrrev_i32_e32 v75, 31, v74
	v_lshlrev_b64 v[74:75], 11, v[74:75]
	v_lshl_add_u64 v[74:75], v[50:51], 0, v[74:75]
	v_mfma_f32_16x16x32_bf16 v[24:27], v[82:85], v[62:65], v[24:27]
	global_store_dword v[74:75], v77, off
	v_mfma_f32_16x16x32_bf16 v[28:31], v[32:35], v[62:65], v[28:31]
	s_cbranch_scc0 .LBB0_823
